# EpiRes row-sum reductions via v_permlane16/32_swap instead of ds_bpermute, on top of previous stack
# speedup vs baseline: 1.0089x; 1.0089x over previous
; #define LAS __attribute__((address_space(3)))
; DI float shx(float v, int m, int lane) { return __builtin_bit_cast(float, __builtin_amdgcn_ds_bpermute((lane ^ m) << 2, __builtin_bit_cast(int, v))); }
; DI unsigned pk2(float lo, float hi) { f32x2_t v = {lo, hi}; bf16x2_t b = __builtin_convertvector(v, bf16x2_t); return __builtin_bit_cast(unsigned, b); }
;     DI void operator()(const f32x4 (&acc)[2][2][4][2], const pg8::Unit& u, int wr, int wc, int fr, int fq) const {
; #pragma unroll
;         for (int ai = 0; ai < 2; ++ai)
; #pragma unroll
;             for (int m = 0; m < 4; ++m) {
;                 const int row = u.pm * 256 + ai * 128 + wr * 64 + m * 16 + fr;
;                 float sq = 0.f;
; #pragma unroll
;                 for (int bj = 0; bj < 2; ++bj) {
;                     const size_t off = (size_t)row * DM + u.pn * 256 + bj * 128 + wc * 32 + 8 * fq;
;                     const u32x4 r = *(const u32x4*)(xb + off);
;                     f32x4 a, b;
;                     a[0] = __builtin_bit_cast(float, r.x << 16); a[1] = __builtin_bit_cast(float, r.x & 0xffff0000u); a[2] = __builtin_bit_cast(float, r.y << 16); a[3] = __builtin_bit_cast(float, r.y & 0xffff0000u);
;                     b[0] = __builtin_bit_cast(float, r.z << 16); b[1] = __builtin_bit_cast(float, r.z & 0xffff0000u); b[2] = __builtin_bit_cast(float, r.w << 16); b[3] = __builtin_bit_cast(float, r.w & 0xffff0000u);
;                     a += acc[ai][bj][m][0]; b += acc[ai][bj][m][1];
;                     if (xout) { *(f32x4*)(xout + off) = a; *(f32x4*)(xout + off + 4) = b; }
;                     else { u32x4 w; w.x = pk2(a[0], a[1]); w.y = pk2(a[2], a[3]); w.z = pk2(b[0], b[1]); w.w = pk2(b[2], b[3]); *(u32x4*)(xb + off) = w; }
;                     sq += (a[0] * a[0] + a[1] * a[1]) + (a[2] * a[2] + a[3] * a[3]) + (b[0] * b[0] + b[1] * b[1]) + (b[2] * b[2] + b[3] * b[3]);
;                 }
;                 if (ssout) { const int lane_ = fq * 16 + fr; sq += shx(sq, 16, lane_); sq += shx(sq, 32, lane_);
;                     if (fq == 0) *(LAS float*)(red + ((ai * 128 + wr * 64 + m * 16 + fr) * 4 + wc) * 4) = sq; }
.LBB0_1155:
	s_lshl_b32 s18, s18, 8
	v_add_u32_e32 v146, s18, v139
	v_ashrrev_i32_e32 v147, 31, v146
	v_readlane_b32 s28, v254, 54
	s_lshl_b32 s20, s20, 8
	v_lshlrev_b64 v[162:163], 12, v[146:147]
	v_readlane_b32 s29, v254, 55
	s_ashr_i32 s21, s20, 31
	v_lshlrev_b32_e32 v0, 1, v138
	v_lshl_add_u64 v[162:163], s[28:29], 0, v[162:163]
	v_lshl_add_u64 v[162:163], s[20:21], 1, v[162:163]
	v_lshl_add_u64 v[166:167], v[162:163], 0, v[0:1]
	s_mov_b32 s23, 0
	global_load_dwordx4 v[172:175], v[166:167], off
	global_load_dwordx4 v[176:179], v[166:167], off offset:256
	s_mov_b32 s22, 0x10000
	v_lshl_add_u64 v[164:165], s[22:23], 0, v[166:167]
	global_load_dwordx4 v[180:183], v[164:165], off
	global_load_dwordx4 v[184:187], v[164:165], off offset:256
	s_mov_b32 s22, 0x20000
	v_lshl_add_u64 v[164:165], s[22:23], 0, v[166:167]
	global_load_dwordx4 v[196:199], v[164:165], off
	global_load_dwordx4 v[200:203], v[164:165], off offset:256
	s_mov_b32 s22, 0x30000
	v_lshl_add_u64 v[164:165], s[22:23], 0, v[166:167]
	global_load_dwordx4 v[204:207], v[164:165], off
	global_load_dwordx4 v[208:211], v[164:165], off offset:256
	s_mov_b32 s22, 0x80000
	v_lshl_add_u64 v[164:165], s[22:23], 0, v[166:167]
	global_load_dwordx4 v[212:215], v[164:165], off
	global_load_dwordx4 v[216:219], v[164:165], off offset:256
	s_mov_b32 s22, 0x90000
	v_lshl_add_u64 v[164:165], s[22:23], 0, v[166:167]
	global_load_dwordx4 v[220:223], v[164:165], off
	global_load_dwordx4 v[224:227], v[164:165], off offset:256
	s_mov_b32 s22, 0xa0000
	v_lshl_add_u64 v[164:165], s[22:23], 0, v[166:167]
	global_load_dwordx4 v[236:239], v[164:165], off
	global_load_dwordx4 v[240:243], v[164:165], off offset:256
	s_mov_b32 s22, 0xb0000
	v_lshl_add_u64 v[164:165], s[22:23], 0, v[166:167]
	global_load_dwordx4 v[244:247], v[164:165], off
	global_load_dwordx4 v[248:251], v[164:165], off offset:256
	s_waitcnt vmcnt(0)
	v_lshlrev_b32_e32 v168, 16, v172
	v_and_b32_e32 v169, 0xffff0000, v172
	v_lshlrev_b32_e32 v162, 16, v173
	v_and_b32_e32 v163, 0xffff0000, v173
	v_lshlrev_b32_e32 v170, 16, v174
	v_and_b32_e32 v171, 0xffff0000, v174
	v_lshlrev_b32_e32 v164, 16, v175
	v_and_b32_e32 v165, 0xffff0000, v175
	v_pk_add_f32 v[128:129], v[128:129], v[162:163]
	v_pk_add_f32 v[126:127], v[126:127], v[168:169]
	v_pk_add_f32 v[162:163], v[124:125], v[164:165]
	v_pk_add_f32 v[164:165], v[122:123], v[170:171]
	v_cvt_pk_bf16_f32 v122, v126, v127
	v_cvt_pk_bf16_f32 v123, v128, v129
	v_cvt_pk_bf16_f32 v124, v164, v165
	v_cvt_pk_bf16_f32 v125, v162, v163
	flat_store_dwordx4 v[166:167], v[122:125]
	s_nop 1
	v_mul_f32_e32 v122, v127, v127
	v_mul_f32_e32 v123, v129, v129
	v_fmac_f32_e32 v122, v126, v126
	v_fmac_f32_e32 v123, v128, v128
	v_add_f32_e32 v122, v122, v123
	v_mul_f32_e32 v123, v165, v165
	v_fmac_f32_e32 v123, v164, v164
	v_add_f32_e32 v122, v123, v122
	v_mul_f32_e32 v123, v163, v163
	v_fmac_f32_e32 v123, v162, v162
	v_add_f32_e32 v147, v123, v122
	v_lshlrev_b32_e32 v126, 16, v176
	v_and_b32_e32 v127, 0xffff0000, v176
	v_lshlrev_b32_e32 v122, 16, v177
	v_and_b32_e32 v123, 0xffff0000, v177
	v_lshlrev_b32_e32 v128, 16, v178
	v_and_b32_e32 v129, 0xffff0000, v178
	v_lshlrev_b32_e32 v124, 16, v179
	v_and_b32_e32 v125, 0xffff0000, v179
	v_pk_add_f32 v[120:121], v[120:121], v[122:123]
	v_pk_add_f32 v[118:119], v[118:119], v[126:127]
	v_pk_add_f32 v[122:123], v[116:117], v[124:125]
	v_pk_add_f32 v[124:125], v[114:115], v[128:129]
	v_cvt_pk_bf16_f32 v114, v118, v119
	v_cvt_pk_bf16_f32 v115, v120, v121
	v_cvt_pk_bf16_f32 v116, v124, v125
	v_cvt_pk_bf16_f32 v117, v122, v123
	flat_store_dwordx4 v[166:167], v[114:117] offset:256
	s_nop 1
	v_mul_f32_e32 v116, v119, v119
	v_mul_f32_e32 v117, v121, v121
	v_mul_f32_e32 v115, v125, v125
	v_fmac_f32_e32 v116, v118, v118
	v_fmac_f32_e32 v117, v120, v120
	v_mul_f32_e32 v114, v123, v123
	v_fmac_f32_e32 v115, v124, v124
	v_add_f32_e32 v116, v116, v117
	v_fmac_f32_e32 v114, v122, v122
	v_add_f32_e32 v115, v115, v116
	v_add_f32_e32 v114, v114, v115
	v_add_f32_e32 v114, v147, v114
	v_mov_b32_e32 v115, v114
	s_nop 1
	v_permlane16_swap_b32_e32 v115, v114
	s_waitcnt lgkmcnt(0)
	v_add_f32_e32 v114, v114, v115
	v_mov_b32_e32 v115, v114
	s_nop 1
	v_permlane32_swap_b32_e32 v115, v114
	s_and_saveexec_b64 s[22:23], s[40:41]
	v_readlane_b32 s54, v254, 62
	s_movk_i32 s53, 0x5880
	v_readlane_b32 s55, v254, 63
	s_cbranch_execz .LBB0_1157
	s_waitcnt lgkmcnt(0)
	v_add_f32_e32 v114, v114, v115
	ds_write_b32 v161, v114
; #define LAS __attribute__((address_space(3)))
; DI float shx(float v, int m, int lane) { return __builtin_bit_cast(float, __builtin_amdgcn_ds_bpermute((lane ^ m) << 2, __builtin_bit_cast(int, v))); }
; DI unsigned pk2(float lo, float hi) { f32x2_t v = {lo, hi}; bf16x2_t b = __builtin_convertvector(v, bf16x2_t); return __builtin_bit_cast(unsigned, b); }
;     DI void operator()(const f32x4 (&acc)[2][2][4][2], const pg8::Unit& u, int wr, int wc, int fr, int fq) const {
;     ...
;             for (int m = 0; m < 4; ++m) {
;                 const int row = u.pm * 256 + ai * 128 + wr * 64 + m * 16 + fr;
;                 float sq = 0.f;
; #pragma unroll
;                 for (int bj = 0; bj < 2; ++bj) {
;                     const size_t off = (size_t)row * DM + u.pn * 256 + bj * 128 + wc * 32 + 8 * fq;
;                     const u32x4 r = *(const u32x4*)(xb + off);
;                     f32x4 a, b;
;                     a[0] = __builtin_bit_cast(float, r.x << 16); a[1] = __builtin_bit_cast(float, r.x & 0xffff0000u); a[2] = __builtin_bit_cast(float, r.y << 16); a[3] = __builtin_bit_cast(float, r.y & 0xffff0000u);
;                     b[0] = __builtin_bit_cast(float, r.z << 16); b[1] = __builtin_bit_cast(float, r.z & 0xffff0000u); b[2] = __builtin_bit_cast(float, r.w << 16); b[3] = __builtin_bit_cast(float, r.w & 0xffff0000u);
;                     a += acc[ai][bj][m][0]; b += acc[ai][bj][m][1];
;                     if (xout) { *(f32x4*)(xout + off) = a; *(f32x4*)(xout + off + 4) = b; }
;                     else { u32x4 w; w.x = pk2(a[0], a[1]); w.y = pk2(a[2], a[3]); w.z = pk2(b[0], b[1]); w.w = pk2(b[2], b[3]); *(u32x4*)(xb + off) = w; }
;                     sq += (a[0] * a[0] + a[1] * a[1]) + (a[2] * a[2] + a[3] * a[3]) + (b[0] * b[0] + b[1] * b[1]) + (b[2] * b[2] + b[3] * b[3]);
;                 }
;                 if (ssout) { const int lane_ = fq * 16 + fr; sq += shx(sq, 16, lane_); sq += shx(sq, 32, lane_);
;                     if (fq == 0) *(LAS float*)(red + ((ai * 128 + wr * 64 + m * 16 + fr) * 4 + wc) * 4) = sq; }
.LBB0_1157:
	s_or_b64 exec, exec, s[22:23]
	v_add_u32_e32 v114, s18, v151
	s_waitcnt lgkmcnt(0)
	v_ashrrev_i32_e32 v115, 31, v114
	v_lshlrev_b64 v[114:115], 12, v[114:115]
	v_lshl_add_u64 v[114:115], s[28:29], 0, v[114:115]
	v_lshl_add_u64 v[114:115], s[20:21], 1, v[114:115]
	v_lshl_add_u64 v[118:119], v[114:115], 0, v[0:1]
	v_lshlrev_b32_e32 v120, 16, v180
	v_and_b32_e32 v121, 0xffff0000, v180
	v_lshlrev_b32_e32 v114, 16, v181
	v_and_b32_e32 v115, 0xffff0000, v181
	v_lshlrev_b32_e32 v122, 16, v182
	v_and_b32_e32 v123, 0xffff0000, v182
	v_lshlrev_b32_e32 v116, 16, v183
	v_and_b32_e32 v117, 0xffff0000, v183
	v_pk_add_f32 v[112:113], v[112:113], v[114:115]
	v_pk_add_f32 v[110:111], v[110:111], v[120:121]
	v_pk_add_f32 v[114:115], v[108:109], v[116:117]
	v_pk_add_f32 v[116:117], v[106:107], v[122:123]
	v_cvt_pk_bf16_f32 v106, v110, v111
	v_cvt_pk_bf16_f32 v107, v112, v113
	v_cvt_pk_bf16_f32 v108, v116, v117
	v_cvt_pk_bf16_f32 v109, v114, v115
	flat_store_dwordx4 v[118:119], v[106:109]
	s_nop 1
	v_mul_f32_e32 v106, v111, v111
	v_mul_f32_e32 v107, v113, v113
	v_fmac_f32_e32 v106, v110, v110
	v_fmac_f32_e32 v107, v112, v112
	v_add_f32_e32 v106, v106, v107
	v_mul_f32_e32 v107, v117, v117
	v_fmac_f32_e32 v107, v116, v116
	v_add_f32_e32 v106, v107, v106
	v_mul_f32_e32 v107, v115, v115
	v_fmac_f32_e32 v107, v114, v114
	v_add_f32_e32 v114, v107, v106
	v_lshlrev_b32_e32 v110, 16, v184
	v_and_b32_e32 v111, 0xffff0000, v184
	v_lshlrev_b32_e32 v106, 16, v185
	v_and_b32_e32 v107, 0xffff0000, v185
	v_lshlrev_b32_e32 v112, 16, v186
	v_and_b32_e32 v113, 0xffff0000, v186
	v_lshlrev_b32_e32 v108, 16, v187
	v_and_b32_e32 v109, 0xffff0000, v187
	v_pk_add_f32 v[104:105], v[104:105], v[106:107]
	v_pk_add_f32 v[102:103], v[102:103], v[110:111]
	v_pk_add_f32 v[106:107], v[100:101], v[108:109]
	v_pk_add_f32 v[108:109], v[98:99], v[112:113]
	v_cvt_pk_bf16_f32 v98, v102, v103
	v_cvt_pk_bf16_f32 v99, v104, v105
	v_cvt_pk_bf16_f32 v100, v108, v109
	v_cvt_pk_bf16_f32 v101, v106, v107
	flat_store_dwordx4 v[118:119], v[98:101] offset:256
	s_nop 1
	v_mul_f32_e32 v100, v103, v103
	v_mul_f32_e32 v101, v105, v105
	v_mul_f32_e32 v99, v109, v109
	v_fmac_f32_e32 v100, v102, v102
	v_fmac_f32_e32 v101, v104, v104
	v_mul_f32_e32 v98, v107, v107
	v_fmac_f32_e32 v99, v108, v108
	v_add_f32_e32 v100, v100, v101
	v_fmac_f32_e32 v98, v106, v106
	v_add_f32_e32 v99, v99, v100
	v_add_f32_e32 v98, v98, v99
	v_add_f32_e32 v98, v114, v98
	v_mov_b32_e32 v99, v98
	s_nop 1
	v_permlane16_swap_b32_e32 v99, v98
	s_waitcnt lgkmcnt(0)
	v_add_f32_e32 v98, v98, v99
	v_mov_b32_e32 v99, v98
	s_nop 1
	v_permlane32_swap_b32_e32 v99, v98
	s_and_saveexec_b64 s[22:23], s[40:41]
	s_cbranch_execz .LBB0_1159
	s_waitcnt lgkmcnt(0)
	v_add_f32_e32 v98, v98, v99
	ds_write_b32 v156, v98
.LBB0_1159:
	s_or_b64 exec, exec, s[22:23]
	v_add_u32_e32 v98, s18, v152
	s_waitcnt lgkmcnt(0)
	v_ashrrev_i32_e32 v99, 31, v98
	v_lshlrev_b64 v[98:99], 12, v[98:99]
	v_lshl_add_u64 v[98:99], s[28:29], 0, v[98:99]
	v_lshl_add_u64 v[98:99], s[20:21], 1, v[98:99]
	v_lshl_add_u64 v[102:103], v[98:99], 0, v[0:1]
	v_lshlrev_b32_e32 v104, 16, v196
	v_and_b32_e32 v105, 0xffff0000, v196
	v_lshlrev_b32_e32 v98, 16, v197
	v_and_b32_e32 v99, 0xffff0000, v197
	v_lshlrev_b32_e32 v106, 16, v198
	v_and_b32_e32 v107, 0xffff0000, v198
	v_lshlrev_b32_e32 v100, 16, v199
	v_and_b32_e32 v101, 0xffff0000, v199
	v_pk_add_f32 v[96:97], v[96:97], v[98:99]
	v_pk_add_f32 v[94:95], v[94:95], v[104:105]
	v_pk_add_f32 v[98:99], v[92:93], v[100:101]
	v_pk_add_f32 v[100:101], v[90:91], v[106:107]
	v_cvt_pk_bf16_f32 v90, v94, v95
	v_cvt_pk_bf16_f32 v91, v96, v97
	v_cvt_pk_bf16_f32 v92, v100, v101
	v_cvt_pk_bf16_f32 v93, v98, v99
	flat_store_dwordx4 v[102:103], v[90:93]
	s_nop 1
	v_mul_f32_e32 v90, v95, v95
	v_mul_f32_e32 v91, v97, v97
	v_fmac_f32_e32 v90, v94, v94
	v_fmac_f32_e32 v91, v96, v96
	v_add_f32_e32 v90, v90, v91
	v_mul_f32_e32 v91, v101, v101
	v_fmac_f32_e32 v91, v100, v100
	v_add_f32_e32 v90, v91, v90
	v_mul_f32_e32 v91, v99, v99
	v_fmac_f32_e32 v91, v98, v98
	v_add_f32_e32 v98, v91, v90
	v_lshlrev_b32_e32 v94, 16, v200
	v_and_b32_e32 v95, 0xffff0000, v200
	v_lshlrev_b32_e32 v90, 16, v201
	v_and_b32_e32 v91, 0xffff0000, v201
	v_lshlrev_b32_e32 v96, 16, v202
	v_and_b32_e32 v97, 0xffff0000, v202
	v_lshlrev_b32_e32 v92, 16, v203
	v_and_b32_e32 v93, 0xffff0000, v203
	v_pk_add_f32 v[88:89], v[88:89], v[90:91]
	v_pk_add_f32 v[86:87], v[86:87], v[94:95]
	v_pk_add_f32 v[90:91], v[84:85], v[92:93]
	v_pk_add_f32 v[92:93], v[82:83], v[96:97]
	v_cvt_pk_bf16_f32 v82, v86, v87
	v_cvt_pk_bf16_f32 v83, v88, v89
	v_cvt_pk_bf16_f32 v84, v92, v93
	v_cvt_pk_bf16_f32 v85, v90, v91
	flat_store_dwordx4 v[102:103], v[82:85] offset:256
	s_nop 1
	v_mul_f32_e32 v84, v87, v87
	v_mul_f32_e32 v85, v89, v89
	v_mul_f32_e32 v83, v93, v93
	v_fmac_f32_e32 v84, v86, v86
	v_fmac_f32_e32 v85, v88, v88
	v_mul_f32_e32 v82, v91, v91
	v_fmac_f32_e32 v83, v92, v92
	v_add_f32_e32 v84, v84, v85
	v_fmac_f32_e32 v82, v90, v90
	v_add_f32_e32 v83, v83, v84
	v_add_f32_e32 v82, v82, v83
	v_add_f32_e32 v82, v98, v82
	v_mov_b32_e32 v83, v82
	s_nop 1
	v_permlane16_swap_b32_e32 v83, v82
	s_waitcnt lgkmcnt(0)
	v_add_f32_e32 v82, v82, v83
	v_mov_b32_e32 v83, v82
	s_nop 1
	v_permlane32_swap_b32_e32 v83, v82
	s_and_saveexec_b64 s[22:23], s[40:41]
	s_cbranch_execz .LBB0_1161
	s_waitcnt lgkmcnt(0)
	v_add_f32_e32 v82, v82, v83
	ds_write_b32 v157, v82
; #define LAS __attribute__((address_space(3)))
; DI float shx(float v, int m, int lane) { return __builtin_bit_cast(float, __builtin_amdgcn_ds_bpermute((lane ^ m) << 2, __builtin_bit_cast(int, v))); }
; DI unsigned pk2(float lo, float hi) { f32x2_t v = {lo, hi}; bf16x2_t b = __builtin_convertvector(v, bf16x2_t); return __builtin_bit_cast(unsigned, b); }
;     DI void operator()(const f32x4 (&acc)[2][2][4][2], const pg8::Unit& u, int wr, int wc, int fr, int fq) const {
;     ...
;             for (int m = 0; m < 4; ++m) {
;                 const int row = u.pm * 256 + ai * 128 + wr * 64 + m * 16 + fr;
;                 float sq = 0.f;
; #pragma unroll
;                 for (int bj = 0; bj < 2; ++bj) {
;                     const size_t off = (size_t)row * DM + u.pn * 256 + bj * 128 + wc * 32 + 8 * fq;
;                     const u32x4 r = *(const u32x4*)(xb + off);
;                     f32x4 a, b;
;                     a[0] = __builtin_bit_cast(float, r.x << 16); a[1] = __builtin_bit_cast(float, r.x & 0xffff0000u); a[2] = __builtin_bit_cast(float, r.y << 16); a[3] = __builtin_bit_cast(float, r.y & 0xffff0000u);
;                     b[0] = __builtin_bit_cast(float, r.z << 16); b[1] = __builtin_bit_cast(float, r.z & 0xffff0000u); b[2] = __builtin_bit_cast(float, r.w << 16); b[3] = __builtin_bit_cast(float, r.w & 0xffff0000u);
;                     a += acc[ai][bj][m][0]; b += acc[ai][bj][m][1];
;                     if (xout) { *(f32x4*)(xout + off) = a; *(f32x4*)(xout + off + 4) = b; }
;                     else { u32x4 w; w.x = pk2(a[0], a[1]); w.y = pk2(a[2], a[3]); w.z = pk2(b[0], b[1]); w.w = pk2(b[2], b[3]); *(u32x4*)(xb + off) = w; }
;                     sq += (a[0] * a[0] + a[1] * a[1]) + (a[2] * a[2] + a[3] * a[3]) + (b[0] * b[0] + b[1] * b[1]) + (b[2] * b[2] + b[3] * b[3]);
;                 }
;                 if (ssout) { const int lane_ = fq * 16 + fr; sq += shx(sq, 16, lane_); sq += shx(sq, 32, lane_);
;                     if (fq == 0) *(LAS float*)(red + ((ai * 128 + wr * 64 + m * 16 + fr) * 4 + wc) * 4) = sq; }
.LBB0_1161:
	s_or_b64 exec, exec, s[22:23]
	v_add_u32_e32 v82, s18, v153
	s_waitcnt lgkmcnt(0)
	v_ashrrev_i32_e32 v83, 31, v82
	v_lshlrev_b64 v[82:83], 12, v[82:83]
	v_lshl_add_u64 v[82:83], s[28:29], 0, v[82:83]
	v_lshl_add_u64 v[82:83], s[20:21], 1, v[82:83]
	v_lshl_add_u64 v[86:87], v[82:83], 0, v[0:1]
	v_lshlrev_b32_e32 v88, 16, v204
	v_and_b32_e32 v89, 0xffff0000, v204
	v_lshlrev_b32_e32 v82, 16, v205
	v_and_b32_e32 v83, 0xffff0000, v205
	v_lshlrev_b32_e32 v90, 16, v206
	v_and_b32_e32 v91, 0xffff0000, v206
	v_lshlrev_b32_e32 v84, 16, v207
	v_and_b32_e32 v85, 0xffff0000, v207
	v_pk_add_f32 v[80:81], v[80:81], v[82:83]
	v_pk_add_f32 v[78:79], v[78:79], v[88:89]
	v_pk_add_f32 v[82:83], v[76:77], v[84:85]
	v_pk_add_f32 v[84:85], v[74:75], v[90:91]
	v_cvt_pk_bf16_f32 v74, v78, v79
	v_cvt_pk_bf16_f32 v75, v80, v81
	v_cvt_pk_bf16_f32 v76, v84, v85
	v_cvt_pk_bf16_f32 v77, v82, v83
	flat_store_dwordx4 v[86:87], v[74:77]
	s_nop 1
	v_mul_f32_e32 v74, v79, v79
	v_mul_f32_e32 v75, v81, v81
	v_fmac_f32_e32 v74, v78, v78
	v_fmac_f32_e32 v75, v80, v80
	v_add_f32_e32 v74, v74, v75
	v_mul_f32_e32 v75, v85, v85
	v_fmac_f32_e32 v75, v84, v84
	v_add_f32_e32 v74, v75, v74
	v_mul_f32_e32 v75, v83, v83
	v_fmac_f32_e32 v75, v82, v82
	v_add_f32_e32 v82, v75, v74
	v_lshlrev_b32_e32 v78, 16, v208
	v_and_b32_e32 v79, 0xffff0000, v208
	v_lshlrev_b32_e32 v74, 16, v209
	v_and_b32_e32 v75, 0xffff0000, v209
	v_lshlrev_b32_e32 v80, 16, v210
	v_and_b32_e32 v81, 0xffff0000, v210
	v_lshlrev_b32_e32 v76, 16, v211
	v_and_b32_e32 v77, 0xffff0000, v211
	v_pk_add_f32 v[72:73], v[72:73], v[74:75]
	v_pk_add_f32 v[70:71], v[70:71], v[78:79]
	v_pk_add_f32 v[74:75], v[68:69], v[76:77]
	v_pk_add_f32 v[76:77], v[66:67], v[80:81]
	v_cvt_pk_bf16_f32 v66, v70, v71
	v_cvt_pk_bf16_f32 v67, v72, v73
	v_cvt_pk_bf16_f32 v68, v76, v77
	v_cvt_pk_bf16_f32 v69, v74, v75
	flat_store_dwordx4 v[86:87], v[66:69] offset:256
	s_nop 1
	v_mul_f32_e32 v68, v71, v71
	v_mul_f32_e32 v69, v73, v73
	v_mul_f32_e32 v67, v77, v77
	v_fmac_f32_e32 v68, v70, v70
	v_fmac_f32_e32 v69, v72, v72
	v_mul_f32_e32 v66, v75, v75
	v_fmac_f32_e32 v67, v76, v76
	v_add_f32_e32 v68, v68, v69
	v_fmac_f32_e32 v66, v74, v74
	v_add_f32_e32 v67, v67, v68
	v_add_f32_e32 v66, v66, v67
	v_add_f32_e32 v66, v82, v66
	v_mov_b32_e32 v67, v66
	s_nop 1
	v_permlane16_swap_b32_e32 v67, v66
	s_waitcnt lgkmcnt(0)
	v_add_f32_e32 v66, v66, v67
	v_mov_b32_e32 v67, v66
	s_nop 1
	v_permlane32_swap_b32_e32 v67, v66
	s_and_saveexec_b64 s[22:23], s[40:41]
	s_cbranch_execz .LBB0_1163
	s_waitcnt lgkmcnt(0)
	v_add_f32_e32 v66, v66, v67
	ds_write_b32 v158, v66
.LBB0_1163:
	s_or_b64 exec, exec, s[22:23]
	v_add_u32_e32 v66, s18, v154
	s_waitcnt lgkmcnt(0)
	v_ashrrev_i32_e32 v67, 31, v66
	v_lshlrev_b64 v[66:67], 12, v[66:67]
	v_lshl_add_u64 v[66:67], s[28:29], 0, v[66:67]
	v_lshl_add_u64 v[66:67], s[20:21], 1, v[66:67]
	v_lshl_add_u64 v[70:71], v[66:67], 0, v[0:1]
	v_lshlrev_b32_e32 v72, 16, v212
	v_and_b32_e32 v73, 0xffff0000, v212
	v_lshlrev_b32_e32 v66, 16, v213
	v_and_b32_e32 v67, 0xffff0000, v213
	v_lshlrev_b32_e32 v74, 16, v214
	v_and_b32_e32 v75, 0xffff0000, v214
	v_lshlrev_b32_e32 v68, 16, v215
	v_and_b32_e32 v69, 0xffff0000, v215
	v_pk_add_f32 v[64:65], v[64:65], v[66:67]
	v_pk_add_f32 v[62:63], v[62:63], v[72:73]
	v_pk_add_f32 v[66:67], v[60:61], v[68:69]
	v_pk_add_f32 v[68:69], v[58:59], v[74:75]
	v_cvt_pk_bf16_f32 v58, v62, v63
	v_cvt_pk_bf16_f32 v59, v64, v65
	v_cvt_pk_bf16_f32 v60, v68, v69
	v_cvt_pk_bf16_f32 v61, v66, v67
	flat_store_dwordx4 v[70:71], v[58:61]
	s_nop 1
	v_mul_f32_e32 v58, v63, v63
	v_mul_f32_e32 v59, v65, v65
	v_fmac_f32_e32 v58, v62, v62
	v_fmac_f32_e32 v59, v64, v64
	v_add_f32_e32 v58, v58, v59
	v_mul_f32_e32 v59, v69, v69
	v_fmac_f32_e32 v59, v68, v68
	v_add_f32_e32 v58, v59, v58
	v_mul_f32_e32 v59, v67, v67
	v_fmac_f32_e32 v59, v66, v66
	v_add_f32_e32 v66, v59, v58
	v_lshlrev_b32_e32 v62, 16, v216
	v_and_b32_e32 v63, 0xffff0000, v216
	v_lshlrev_b32_e32 v58, 16, v217
	v_and_b32_e32 v59, 0xffff0000, v217
	v_lshlrev_b32_e32 v64, 16, v218
	v_and_b32_e32 v65, 0xffff0000, v218
	v_lshlrev_b32_e32 v60, 16, v219
	v_and_b32_e32 v61, 0xffff0000, v219
	v_pk_add_f32 v[56:57], v[56:57], v[58:59]
	v_pk_add_f32 v[54:55], v[54:55], v[62:63]
	v_pk_add_f32 v[58:59], v[52:53], v[60:61]
	v_pk_add_f32 v[60:61], v[50:51], v[64:65]
	v_cvt_pk_bf16_f32 v50, v54, v55
	v_cvt_pk_bf16_f32 v51, v56, v57
	v_cvt_pk_bf16_f32 v52, v60, v61
	v_cvt_pk_bf16_f32 v53, v58, v59
	flat_store_dwordx4 v[70:71], v[50:53] offset:256
	s_nop 1
	v_mul_f32_e32 v52, v55, v55
	v_mul_f32_e32 v53, v57, v57
	v_mul_f32_e32 v51, v61, v61
	v_fmac_f32_e32 v52, v54, v54
	v_fmac_f32_e32 v53, v56, v56
	v_mul_f32_e32 v50, v59, v59
	v_fmac_f32_e32 v51, v60, v60
	v_add_f32_e32 v52, v52, v53
	v_fmac_f32_e32 v50, v58, v58
	v_add_f32_e32 v51, v51, v52
	v_add_f32_e32 v50, v50, v51
	v_add_f32_e32 v50, v66, v50
	v_mov_b32_e32 v51, v50
	s_nop 1
	v_permlane16_swap_b32_e32 v51, v50
	s_waitcnt lgkmcnt(0)
	v_add_f32_e32 v50, v50, v51
	v_mov_b32_e32 v51, v50
	s_nop 1
	v_permlane32_swap_b32_e32 v51, v50
	s_and_saveexec_b64 s[22:23], s[40:41]
	s_cbranch_execz .LBB0_1165
	s_waitcnt lgkmcnt(0)
	v_add_f32_e32 v50, v50, v51
	ds_write_b32 v159, v50
; #define LAS __attribute__((address_space(3)))
; DI float shx(float v, int m, int lane) { return __builtin_bit_cast(float, __builtin_amdgcn_ds_bpermute((lane ^ m) << 2, __builtin_bit_cast(int, v))); }
; DI unsigned pk2(float lo, float hi) { f32x2_t v = {lo, hi}; bf16x2_t b = __builtin_convertvector(v, bf16x2_t); return __builtin_bit_cast(unsigned, b); }
;     DI void operator()(const f32x4 (&acc)[2][2][4][2], const pg8::Unit& u, int wr, int wc, int fr, int fq) const {
;     ...
;             for (int m = 0; m < 4; ++m) {
;                 const int row = u.pm * 256 + ai * 128 + wr * 64 + m * 16 + fr;
;                 float sq = 0.f;
; #pragma unroll
;                 for (int bj = 0; bj < 2; ++bj) {
;                     const size_t off = (size_t)row * DM + u.pn * 256 + bj * 128 + wc * 32 + 8 * fq;
;                     const u32x4 r = *(const u32x4*)(xb + off);
;                     f32x4 a, b;
;                     a[0] = __builtin_bit_cast(float, r.x << 16); a[1] = __builtin_bit_cast(float, r.x & 0xffff0000u); a[2] = __builtin_bit_cast(float, r.y << 16); a[3] = __builtin_bit_cast(float, r.y & 0xffff0000u);
;                     b[0] = __builtin_bit_cast(float, r.z << 16); b[1] = __builtin_bit_cast(float, r.z & 0xffff0000u); b[2] = __builtin_bit_cast(float, r.w << 16); b[3] = __builtin_bit_cast(float, r.w & 0xffff0000u);
;                     a += acc[ai][bj][m][0]; b += acc[ai][bj][m][1];
;                     if (xout) { *(f32x4*)(xout + off) = a; *(f32x4*)(xout + off + 4) = b; }
;                     else { u32x4 w; w.x = pk2(a[0], a[1]); w.y = pk2(a[2], a[3]); w.z = pk2(b[0], b[1]); w.w = pk2(b[2], b[3]); *(u32x4*)(xb + off) = w; }
;                     sq += (a[0] * a[0] + a[1] * a[1]) + (a[2] * a[2] + a[3] * a[3]) + (b[0] * b[0] + b[1] * b[1]) + (b[2] * b[2] + b[3] * b[3]);
;                 }
;                 if (ssout) { const int lane_ = fq * 16 + fr; sq += shx(sq, 16, lane_); sq += shx(sq, 32, lane_);
;                     if (fq == 0) *(LAS float*)(red + ((ai * 128 + wr * 64 + m * 16 + fr) * 4 + wc) * 4) = sq; }
.LBB0_1165:
	s_or_b64 exec, exec, s[22:23]
	v_add_u32_e32 v50, 0x90, v146
	s_waitcnt lgkmcnt(0)
	v_ashrrev_i32_e32 v51, 31, v50
	v_lshlrev_b64 v[50:51], 12, v[50:51]
	v_lshl_add_u64 v[50:51], s[28:29], 0, v[50:51]
	v_lshl_add_u64 v[50:51], s[20:21], 1, v[50:51]
	v_lshl_add_u64 v[54:55], v[50:51], 0, v[0:1]
	v_lshlrev_b32_e32 v56, 16, v220
	v_and_b32_e32 v57, 0xffff0000, v220
	v_lshlrev_b32_e32 v50, 16, v221
	v_and_b32_e32 v51, 0xffff0000, v221
	v_lshlrev_b32_e32 v58, 16, v222
	v_and_b32_e32 v59, 0xffff0000, v222
	v_lshlrev_b32_e32 v52, 16, v223
	v_and_b32_e32 v53, 0xffff0000, v223
	v_pk_add_f32 v[48:49], v[48:49], v[50:51]
	v_pk_add_f32 v[46:47], v[46:47], v[56:57]
	v_pk_add_f32 v[50:51], v[44:45], v[52:53]
	v_pk_add_f32 v[52:53], v[42:43], v[58:59]
	v_cvt_pk_bf16_f32 v42, v46, v47
	v_cvt_pk_bf16_f32 v43, v48, v49
	v_cvt_pk_bf16_f32 v44, v52, v53
	v_cvt_pk_bf16_f32 v45, v50, v51
	flat_store_dwordx4 v[54:55], v[42:45]
	s_nop 1
	v_mul_f32_e32 v42, v47, v47
	v_mul_f32_e32 v43, v49, v49
	v_fmac_f32_e32 v42, v46, v46
	v_fmac_f32_e32 v43, v48, v48
	v_add_f32_e32 v42, v42, v43
	v_mul_f32_e32 v43, v53, v53
	v_fmac_f32_e32 v43, v52, v52
	v_add_f32_e32 v42, v43, v42
	v_mul_f32_e32 v43, v51, v51
	v_fmac_f32_e32 v43, v50, v50
	v_add_f32_e32 v50, v43, v42
	v_lshlrev_b32_e32 v46, 16, v224
	v_and_b32_e32 v47, 0xffff0000, v224
	v_lshlrev_b32_e32 v42, 16, v225
	v_and_b32_e32 v43, 0xffff0000, v225
	v_lshlrev_b32_e32 v48, 16, v226
	v_and_b32_e32 v49, 0xffff0000, v226
	v_lshlrev_b32_e32 v44, 16, v227
	v_and_b32_e32 v45, 0xffff0000, v227
	v_pk_add_f32 v[40:41], v[40:41], v[42:43]
	v_pk_add_f32 v[38:39], v[38:39], v[46:47]
	v_pk_add_f32 v[42:43], v[36:37], v[44:45]
	v_pk_add_f32 v[44:45], v[34:35], v[48:49]
	v_cvt_pk_bf16_f32 v34, v38, v39
	v_cvt_pk_bf16_f32 v35, v40, v41
	v_cvt_pk_bf16_f32 v36, v44, v45
	v_cvt_pk_bf16_f32 v37, v42, v43
	flat_store_dwordx4 v[54:55], v[34:37] offset:256
	s_nop 1
	v_mul_f32_e32 v36, v39, v39
	v_mul_f32_e32 v37, v41, v41
	v_mul_f32_e32 v35, v45, v45
	v_fmac_f32_e32 v36, v38, v38
	v_fmac_f32_e32 v37, v40, v40
	v_mul_f32_e32 v34, v43, v43
	v_fmac_f32_e32 v35, v44, v44
	v_add_f32_e32 v36, v36, v37
	v_fmac_f32_e32 v34, v42, v42
	v_add_f32_e32 v35, v35, v36
	v_add_f32_e32 v34, v34, v35
	v_add_f32_e32 v34, v50, v34
	v_mov_b32_e32 v35, v34
	s_nop 1
	v_permlane16_swap_b32_e32 v35, v34
	s_waitcnt lgkmcnt(0)
	v_add_f32_e32 v34, v34, v35
	v_mov_b32_e32 v35, v34
	s_nop 1
	v_permlane32_swap_b32_e32 v35, v34
	s_and_saveexec_b64 s[22:23], s[40:41]
	s_cbranch_execz .LBB0_1167
	s_waitcnt lgkmcnt(0)
	v_add_f32_e32 v34, v34, v35
	ds_write_b32 v161, v34 offset:2304
; #define LAS __attribute__((address_space(3)))
; DI float shx(float v, int m, int lane) { return __builtin_bit_cast(float, __builtin_amdgcn_ds_bpermute((lane ^ m) << 2, __builtin_bit_cast(int, v))); }
; DI unsigned pk2(float lo, float hi) { f32x2_t v = {lo, hi}; bf16x2_t b = __builtin_convertvector(v, bf16x2_t); return __builtin_bit_cast(unsigned, b); }
;     DI void operator()(const f32x4 (&acc)[2][2][4][2], const pg8::Unit& u, int wr, int wc, int fr, int fq) const {
;     ...
;             for (int m = 0; m < 4; ++m) {
;                 const int row = u.pm * 256 + ai * 128 + wr * 64 + m * 16 + fr;
;                 float sq = 0.f;
; #pragma unroll
;                 for (int bj = 0; bj < 2; ++bj) {
;                     const size_t off = (size_t)row * DM + u.pn * 256 + bj * 128 + wc * 32 + 8 * fq;
;                     const u32x4 r = *(const u32x4*)(xb + off);
;                     f32x4 a, b;
;                     a[0] = __builtin_bit_cast(float, r.x << 16); a[1] = __builtin_bit_cast(float, r.x & 0xffff0000u); a[2] = __builtin_bit_cast(float, r.y << 16); a[3] = __builtin_bit_cast(float, r.y & 0xffff0000u);
;                     b[0] = __builtin_bit_cast(float, r.z << 16); b[1] = __builtin_bit_cast(float, r.z & 0xffff0000u); b[2] = __builtin_bit_cast(float, r.w << 16); b[3] = __builtin_bit_cast(float, r.w & 0xffff0000u);
;                     a += acc[ai][bj][m][0]; b += acc[ai][bj][m][1];
;                     if (xout) { *(f32x4*)(xout + off) = a; *(f32x4*)(xout + off + 4) = b; }
;                     else { u32x4 w; w.x = pk2(a[0], a[1]); w.y = pk2(a[2], a[3]); w.z = pk2(b[0], b[1]); w.w = pk2(b[2], b[3]); *(u32x4*)(xb + off) = w; }
;                     sq += (a[0] * a[0] + a[1] * a[1]) + (a[2] * a[2] + a[3] * a[3]) + (b[0] * b[0] + b[1] * b[1]) + (b[2] * b[2] + b[3] * b[3]);
;                 }
;                 if (ssout) { const int lane_ = fq * 16 + fr; sq += shx(sq, 16, lane_); sq += shx(sq, 32, lane_);
;                     if (fq == 0) *(LAS float*)(red + ((ai * 128 + wr * 64 + m * 16 + fr) * 4 + wc) * 4) = sq; }
.LBB0_1167:
	s_or_b64 exec, exec, s[22:23]
	v_add_u32_e32 v34, 0xa0, v146
	s_waitcnt lgkmcnt(0)
	v_ashrrev_i32_e32 v35, 31, v34
	v_lshlrev_b64 v[34:35], 12, v[34:35]
	v_lshl_add_u64 v[34:35], s[28:29], 0, v[34:35]
	v_lshl_add_u64 v[34:35], s[20:21], 1, v[34:35]
	v_lshl_add_u64 v[38:39], v[34:35], 0, v[0:1]
	v_lshlrev_b32_e32 v40, 16, v236
	v_and_b32_e32 v41, 0xffff0000, v236
	v_lshlrev_b32_e32 v34, 16, v237
	v_and_b32_e32 v35, 0xffff0000, v237
	v_lshlrev_b32_e32 v42, 16, v238
	v_and_b32_e32 v43, 0xffff0000, v238
	v_lshlrev_b32_e32 v36, 16, v239
	v_and_b32_e32 v37, 0xffff0000, v239
	v_pk_add_f32 v[32:33], v[32:33], v[34:35]
	v_pk_add_f32 v[30:31], v[30:31], v[40:41]
	v_pk_add_f32 v[34:35], v[28:29], v[36:37]
	v_pk_add_f32 v[36:37], v[26:27], v[42:43]
	v_cvt_pk_bf16_f32 v26, v30, v31
	v_cvt_pk_bf16_f32 v27, v32, v33
	v_cvt_pk_bf16_f32 v28, v36, v37
	v_cvt_pk_bf16_f32 v29, v34, v35
	flat_store_dwordx4 v[38:39], v[26:29]
	s_nop 1
	v_mul_f32_e32 v26, v31, v31
	v_mul_f32_e32 v27, v33, v33
	v_fmac_f32_e32 v26, v30, v30
	v_fmac_f32_e32 v27, v32, v32
	v_add_f32_e32 v26, v26, v27
	v_mul_f32_e32 v27, v37, v37
	v_fmac_f32_e32 v27, v36, v36
	v_add_f32_e32 v26, v27, v26
	v_mul_f32_e32 v27, v35, v35
	v_fmac_f32_e32 v27, v34, v34
	v_add_f32_e32 v34, v27, v26
	v_lshlrev_b32_e32 v30, 16, v240
	v_and_b32_e32 v31, 0xffff0000, v240
	v_lshlrev_b32_e32 v26, 16, v241
	v_and_b32_e32 v27, 0xffff0000, v241
	v_lshlrev_b32_e32 v32, 16, v242
	v_and_b32_e32 v33, 0xffff0000, v242
	v_lshlrev_b32_e32 v28, 16, v243
	v_and_b32_e32 v29, 0xffff0000, v243
	v_pk_add_f32 v[24:25], v[24:25], v[26:27]
	v_pk_add_f32 v[22:23], v[22:23], v[30:31]
	v_pk_add_f32 v[26:27], v[20:21], v[28:29]
	v_pk_add_f32 v[28:29], v[18:19], v[32:33]
	v_cvt_pk_bf16_f32 v18, v22, v23
	v_cvt_pk_bf16_f32 v19, v24, v25
	v_cvt_pk_bf16_f32 v20, v28, v29
	v_cvt_pk_bf16_f32 v21, v26, v27
	flat_store_dwordx4 v[38:39], v[18:21] offset:256
	s_nop 1
	v_mul_f32_e32 v20, v23, v23
	v_mul_f32_e32 v21, v25, v25
	v_mul_f32_e32 v19, v29, v29
	v_fmac_f32_e32 v20, v22, v22
	v_fmac_f32_e32 v21, v24, v24
	v_mul_f32_e32 v18, v27, v27
	v_fmac_f32_e32 v19, v28, v28
	v_add_f32_e32 v20, v20, v21
	v_fmac_f32_e32 v18, v26, v26
	v_add_f32_e32 v19, v19, v20
	v_add_f32_e32 v18, v18, v19
	v_add_f32_e32 v18, v34, v18
	v_mov_b32_e32 v19, v18
	s_nop 1
	v_permlane16_swap_b32_e32 v19, v18
	s_waitcnt lgkmcnt(0)
	v_add_f32_e32 v18, v18, v19
	v_mov_b32_e32 v19, v18
	s_nop 1
	v_permlane32_swap_b32_e32 v19, v18
	s_and_saveexec_b64 s[22:23], s[40:41]
	s_cbranch_execz .LBB0_1169
	s_waitcnt lgkmcnt(0)
	v_add_f32_e32 v18, v18, v19
	ds_write_b32 v161, v18 offset:2560
.LBB0_1169:
	s_or_b64 exec, exec, s[22:23]
	v_add_u32_e32 v18, 0xb0, v146
	s_waitcnt lgkmcnt(0)
	v_ashrrev_i32_e32 v19, 31, v18
	v_lshlrev_b64 v[18:19], 12, v[18:19]
	v_lshl_add_u64 v[18:19], s[28:29], 0, v[18:19]
	v_lshl_add_u64 v[18:19], s[20:21], 1, v[18:19]
	v_lshl_add_u64 v[22:23], v[18:19], 0, v[0:1]
	v_lshlrev_b32_e32 v24, 16, v244
	v_and_b32_e32 v25, 0xffff0000, v244
	v_lshlrev_b32_e32 v18, 16, v245
	v_and_b32_e32 v19, 0xffff0000, v245
	v_lshlrev_b32_e32 v26, 16, v246
	v_and_b32_e32 v27, 0xffff0000, v246
	v_lshlrev_b32_e32 v20, 16, v247
	v_and_b32_e32 v21, 0xffff0000, v247
	v_pk_add_f32 v[16:17], v[16:17], v[18:19]
	v_pk_add_f32 v[14:15], v[14:15], v[24:25]
	v_pk_add_f32 v[18:19], v[12:13], v[20:21]
	v_pk_add_f32 v[20:21], v[10:11], v[26:27]
	v_cvt_pk_bf16_f32 v10, v14, v15
	v_cvt_pk_bf16_f32 v11, v16, v17
	v_cvt_pk_bf16_f32 v12, v20, v21
	v_cvt_pk_bf16_f32 v13, v18, v19
	flat_store_dwordx4 v[22:23], v[10:13]
	v_mul_f32_e32 v0, v15, v15
	v_fmac_f32_e32 v0, v14, v14
	v_mul_f32_e32 v10, v17, v17
	v_fmac_f32_e32 v10, v16, v16
	v_add_f32_e32 v0, v0, v10
	v_mul_f32_e32 v10, v21, v21
	v_fmac_f32_e32 v10, v20, v20
	v_add_f32_e32 v0, v10, v0
	v_mul_f32_e32 v10, v19, v19
	v_fmac_f32_e32 v10, v18, v18
	v_add_f32_e32 v0, v10, v0
	v_lshlrev_b32_e32 v14, 16, v248
	v_and_b32_e32 v15, 0xffff0000, v248
	v_lshlrev_b32_e32 v10, 16, v249
	v_and_b32_e32 v11, 0xffff0000, v249
	v_lshlrev_b32_e32 v16, 16, v250
	v_and_b32_e32 v17, 0xffff0000, v250
	v_lshlrev_b32_e32 v12, 16, v251
	v_and_b32_e32 v13, 0xffff0000, v251
	v_pk_add_f32 v[8:9], v[8:9], v[10:11]
	v_pk_add_f32 v[6:7], v[6:7], v[14:15]
	v_pk_add_f32 v[10:11], v[4:5], v[12:13]
	v_pk_add_f32 v[12:13], v[2:3], v[16:17]
	v_cvt_pk_bf16_f32 v2, v6, v7
	v_cvt_pk_bf16_f32 v3, v8, v9
	v_cvt_pk_bf16_f32 v4, v12, v13
	v_cvt_pk_bf16_f32 v5, v10, v11
	flat_store_dwordx4 v[22:23], v[2:5] offset:256
	s_nop 1
	v_mul_f32_e32 v4, v7, v7
	v_mul_f32_e32 v5, v9, v9
	v_mul_f32_e32 v3, v13, v13
	v_fmac_f32_e32 v4, v6, v6
	v_fmac_f32_e32 v5, v8, v8
	v_mul_f32_e32 v2, v11, v11
	v_fmac_f32_e32 v3, v12, v12
	v_add_f32_e32 v4, v4, v5
	v_fmac_f32_e32 v2, v10, v10
	v_add_f32_e32 v3, v3, v4
	v_add_f32_e32 v2, v2, v3
	v_add_f32_e32 v0, v0, v2
	v_mov_b32_e32 v2, v0
	s_nop 1
	v_permlane16_swap_b32_e32 v2, v0
	s_waitcnt lgkmcnt(0)
	v_add_f32_e32 v0, v0, v2
	v_mov_b32_e32 v2, v0
	s_nop 1
	v_permlane32_swap_b32_e32 v2, v0
	s_and_saveexec_b64 s[20:21], s[40:41]
	s_cbranch_execz .LBB0_1171
	s_waitcnt lgkmcnt(0)
	v_add_f32_e32 v0, v0, v2
	ds_write_b32 v161, v0 offset:2816

; #define LAS __attribute__((address_space(3)))
; DI float shx(float v, int m, int lane) { return __builtin_bit_cast(float, __builtin_amdgcn_ds_bpermute((lane ^ m) << 2, __builtin_bit_cast(int, v))); }
;     DI void operator()(const f32x4 (&acc)[2][2][4][2], const pg8::Unit& u, int wr, int wc, int fr, int fq) const {
;     ...
;                     sq += (a[0] * a[0] + a[1] * a[1]) + (a[2] * a[2] + a[3] * a[3]) + (b[0] * b[0] + b[1] * b[1]) + (b[2] * b[2] + b[3] * b[3]);
;                 }
;                 if (ssout) { const int lane_ = fq * 16 + fr; sq += shx(sq, 16, lane_); sq += shx(sq, 32, lane_);
;                     if (fq == 0) *(LAS float*)(red + ((ai * 128 + wr * 64 + m * 16 + fr) * 4 + wc) * 4) = sq; }
.LBB0_1333:
	v_readlane_b32 s22, v254, 36
	v_readlane_b32 s23, v254, 37
	s_andn2_b64 vcc, exec, s[22:23]
	s_nop 0
	v_cndmask_b32_e64 v145, 0, 1, s[22:23]
	v_cmp_ne_u32_e64 s[4:5], 1, v145
	s_cbranch_vccnz .LBB0_1337
	v_mul_f32_e32 v127, v127, v127
	v_fmac_f32_e32 v127, v126, v126
	v_mul_f32_e32 v126, v129, v129
	v_mul_f32_e32 v117, v117, v117
	v_mul_f32_e32 v115, v115, v115
	v_fmac_f32_e32 v126, v128, v128
	v_mul_f32_e32 v123, v123, v123
	v_fmac_f32_e32 v117, v116, v116
	v_fmac_f32_e32 v115, v114, v114
	v_mul_f32_e32 v114, v119, v119
	v_mul_f32_e32 v116, v121, v121
	v_add_f32_e32 v126, v127, v126
	v_fmac_f32_e32 v123, v122, v122
	v_fmac_f32_e32 v114, v118, v118
	v_fmac_f32_e32 v116, v120, v120
	v_add_f32_e32 v122, v123, v126
	v_mul_f32_e32 v123, v125, v125
	v_add_f32_e32 v114, v114, v116
	v_fmac_f32_e32 v123, v124, v124
	v_add_f32_e32 v114, v115, v114
	v_add_f32_e32 v122, v123, v122
	v_add_f32_e32 v114, v117, v114
	v_add_f32_e32 v114, v122, v114
	v_mov_b32_e32 v115, v114
	s_nop 1
	v_permlane16_swap_b32_e32 v115, v114
	s_waitcnt lgkmcnt(0)
	v_add_f32_e32 v114, v114, v115
	v_mov_b32_e32 v115, v114
	s_nop 1
	v_permlane32_swap_b32_e32 v115, v114
	s_and_saveexec_b64 s[22:23], s[38:39]
	s_cbranch_execz .LBB0_1336
	s_waitcnt lgkmcnt(0)
	v_add_f32_e32 v114, v114, v115
	v_add_u32_e32 v115, s35, v159
	ds_write_b32 v115, v114

; #define LAS __attribute__((address_space(3)))
; DI float shx(float v, int m, int lane) { return __builtin_bit_cast(float, __builtin_amdgcn_ds_bpermute((lane ^ m) << 2, __builtin_bit_cast(int, v))); }
;     DI void operator()(const f32x4 (&acc)[2][2][4][2], const pg8::Unit& u, int wr, int wc, int fr, int fq) const {
;     ...
;                     sq += (a[0] * a[0] + a[1] * a[1]) + (a[2] * a[2] + a[3] * a[3]) + (b[0] * b[0] + b[1] * b[1]) + (b[2] * b[2] + b[3] * b[3]);
;                 }
;                 if (ssout) { const int lane_ = fq * 16 + fr; sq += shx(sq, 16, lane_); sq += shx(sq, 32, lane_);
;                     if (fq == 0) *(LAS float*)(red + ((ai * 128 + wr * 64 + m * 16 + fr) * 4 + wc) * 4) = sq; }
.LBB0_1343:
	s_and_b64 vcc, exec, s[4:5]
	s_cbranch_vccnz .LBB0_1347
	v_mul_f32_e32 v111, v111, v111
	v_fmac_f32_e32 v111, v110, v110
	v_mul_f32_e32 v110, v113, v113
	v_mul_f32_e32 v101, v101, v101
	v_mul_f32_e32 v99, v99, v99
	v_fmac_f32_e32 v110, v112, v112
	v_mul_f32_e32 v107, v107, v107
	v_fmac_f32_e32 v101, v100, v100
	v_fmac_f32_e32 v99, v98, v98
	v_mul_f32_e32 v98, v103, v103
	v_mul_f32_e32 v100, v105, v105
	v_add_f32_e32 v110, v111, v110
	v_fmac_f32_e32 v107, v106, v106
	v_fmac_f32_e32 v98, v102, v102
	v_fmac_f32_e32 v100, v104, v104
	v_add_f32_e32 v106, v107, v110
	v_mul_f32_e32 v107, v109, v109
	v_add_f32_e32 v98, v98, v100
	v_fmac_f32_e32 v107, v108, v108
	v_add_f32_e32 v98, v99, v98
	v_add_f32_e32 v106, v107, v106
	v_add_f32_e32 v98, v101, v98
	v_add_f32_e32 v98, v106, v98
	v_mov_b32_e32 v99, v98
	s_nop 1
	v_permlane16_swap_b32_e32 v99, v98
	s_waitcnt lgkmcnt(0)
	v_add_f32_e32 v98, v98, v99
	v_mov_b32_e32 v99, v98
	s_nop 1
	v_permlane32_swap_b32_e32 v99, v98
	s_and_saveexec_b64 s[22:23], s[38:39]
	s_cbranch_execz .LBB0_1346
	s_waitcnt lgkmcnt(0)
	v_add_f32_e32 v98, v98, v99
	ds_write_b32 v161, v98

; #define LAS __attribute__((address_space(3)))
; DI float shx(float v, int m, int lane) { return __builtin_bit_cast(float, __builtin_amdgcn_ds_bpermute((lane ^ m) << 2, __builtin_bit_cast(int, v))); }
;     DI void operator()(const f32x4 (&acc)[2][2][4][2], const pg8::Unit& u, int wr, int wc, int fr, int fq) const {
;     ...
;                     sq += (a[0] * a[0] + a[1] * a[1]) + (a[2] * a[2] + a[3] * a[3]) + (b[0] * b[0] + b[1] * b[1]) + (b[2] * b[2] + b[3] * b[3]);
;                 }
;                 if (ssout) { const int lane_ = fq * 16 + fr; sq += shx(sq, 16, lane_); sq += shx(sq, 32, lane_);
;                     if (fq == 0) *(LAS float*)(red + ((ai * 128 + wr * 64 + m * 16 + fr) * 4 + wc) * 4) = sq; }
.LBB0_1353:
	s_and_b64 vcc, exec, s[4:5]
	s_cbranch_vccnz .LBB0_1357
	v_mul_f32_e32 v95, v95, v95
	v_fmac_f32_e32 v95, v94, v94
	v_mul_f32_e32 v94, v97, v97
	v_mul_f32_e32 v85, v85, v85
	v_mul_f32_e32 v83, v83, v83
	v_fmac_f32_e32 v94, v96, v96
	v_mul_f32_e32 v91, v91, v91
	v_fmac_f32_e32 v85, v84, v84
	v_fmac_f32_e32 v83, v82, v82
	v_mul_f32_e32 v82, v87, v87
	v_mul_f32_e32 v84, v89, v89
	v_add_f32_e32 v94, v95, v94
	v_fmac_f32_e32 v91, v90, v90
	v_fmac_f32_e32 v82, v86, v86
	v_fmac_f32_e32 v84, v88, v88
	v_add_f32_e32 v90, v91, v94
	v_mul_f32_e32 v91, v93, v93
	v_add_f32_e32 v82, v82, v84
	v_fmac_f32_e32 v91, v92, v92
	v_add_f32_e32 v82, v83, v82
	v_add_f32_e32 v90, v91, v90
	v_add_f32_e32 v82, v85, v82
	v_add_f32_e32 v82, v90, v82
	v_mov_b32_e32 v83, v82
	s_nop 1
	v_permlane16_swap_b32_e32 v83, v82
	s_waitcnt lgkmcnt(0)
	v_add_f32_e32 v82, v82, v83
	v_mov_b32_e32 v83, v82
	s_nop 1
	v_permlane32_swap_b32_e32 v83, v82
	s_and_saveexec_b64 s[22:23], s[38:39]
	s_cbranch_execz .LBB0_1356
	s_waitcnt lgkmcnt(0)
	v_add_f32_e32 v82, v82, v83
	ds_write_b32 v162, v82

; #define LAS __attribute__((address_space(3)))
; DI float shx(float v, int m, int lane) { return __builtin_bit_cast(float, __builtin_amdgcn_ds_bpermute((lane ^ m) << 2, __builtin_bit_cast(int, v))); }
;     DI void operator()(const f32x4 (&acc)[2][2][4][2], const pg8::Unit& u, int wr, int wc, int fr, int fq) const {
;     ...
;                     sq += (a[0] * a[0] + a[1] * a[1]) + (a[2] * a[2] + a[3] * a[3]) + (b[0] * b[0] + b[1] * b[1]) + (b[2] * b[2] + b[3] * b[3]);
;                 }
;                 if (ssout) { const int lane_ = fq * 16 + fr; sq += shx(sq, 16, lane_); sq += shx(sq, 32, lane_);
;                     if (fq == 0) *(LAS float*)(red + ((ai * 128 + wr * 64 + m * 16 + fr) * 4 + wc) * 4) = sq; }
.LBB0_1363:
	s_and_b64 vcc, exec, s[4:5]
	s_cbranch_vccnz .LBB0_1367
	v_mul_f32_e32 v79, v79, v79
	v_fmac_f32_e32 v79, v78, v78
	v_mul_f32_e32 v78, v81, v81
	v_mul_f32_e32 v69, v69, v69
	v_mul_f32_e32 v67, v67, v67
	v_fmac_f32_e32 v78, v80, v80
	v_mul_f32_e32 v75, v75, v75
	v_fmac_f32_e32 v69, v68, v68
	v_fmac_f32_e32 v67, v66, v66
	v_mul_f32_e32 v66, v71, v71
	v_mul_f32_e32 v68, v73, v73
	v_add_f32_e32 v78, v79, v78
	v_fmac_f32_e32 v75, v74, v74
	v_fmac_f32_e32 v66, v70, v70
	v_fmac_f32_e32 v68, v72, v72
	v_add_f32_e32 v74, v75, v78
	v_mul_f32_e32 v75, v77, v77
	v_add_f32_e32 v66, v66, v68
	v_fmac_f32_e32 v75, v76, v76
	v_add_f32_e32 v66, v67, v66
	v_add_f32_e32 v74, v75, v74
	v_add_f32_e32 v66, v69, v66
	v_add_f32_e32 v66, v74, v66
	v_mov_b32_e32 v67, v66
	s_nop 1
	v_permlane16_swap_b32_e32 v67, v66
	s_waitcnt lgkmcnt(0)
	v_add_f32_e32 v66, v66, v67
	v_mov_b32_e32 v67, v66
	s_nop 1
	v_permlane32_swap_b32_e32 v67, v66
	s_and_saveexec_b64 s[22:23], s[38:39]
	s_cbranch_execz .LBB0_1366
	s_waitcnt lgkmcnt(0)
	v_add_f32_e32 v66, v66, v67
	ds_write_b32 v163, v66

; #define LAS __attribute__((address_space(3)))
; DI float shx(float v, int m, int lane) { return __builtin_bit_cast(float, __builtin_amdgcn_ds_bpermute((lane ^ m) << 2, __builtin_bit_cast(int, v))); }
;     DI void operator()(const f32x4 (&acc)[2][2][4][2], const pg8::Unit& u, int wr, int wc, int fr, int fq) const {
;     ...
;                     sq += (a[0] * a[0] + a[1] * a[1]) + (a[2] * a[2] + a[3] * a[3]) + (b[0] * b[0] + b[1] * b[1]) + (b[2] * b[2] + b[3] * b[3]);
;                 }
;                 if (ssout) { const int lane_ = fq * 16 + fr; sq += shx(sq, 16, lane_); sq += shx(sq, 32, lane_);
;                     if (fq == 0) *(LAS float*)(red + ((ai * 128 + wr * 64 + m * 16 + fr) * 4 + wc) * 4) = sq; }
.LBB0_1373:
	s_and_b64 vcc, exec, s[4:5]
	s_cbranch_vccnz .LBB0_1377
	v_mul_f32_e32 v63, v63, v63
	v_fmac_f32_e32 v63, v62, v62
	v_mul_f32_e32 v62, v65, v65
	v_mul_f32_e32 v53, v53, v53
	v_mul_f32_e32 v51, v51, v51
	v_fmac_f32_e32 v62, v64, v64
	v_mul_f32_e32 v59, v59, v59
	v_fmac_f32_e32 v53, v52, v52
	v_fmac_f32_e32 v51, v50, v50
	v_mul_f32_e32 v50, v55, v55
	v_mul_f32_e32 v52, v57, v57
	v_add_f32_e32 v62, v63, v62
	v_fmac_f32_e32 v59, v58, v58
	v_fmac_f32_e32 v50, v54, v54
	v_fmac_f32_e32 v52, v56, v56
	v_add_f32_e32 v58, v59, v62
	v_mul_f32_e32 v59, v61, v61
	v_add_f32_e32 v50, v50, v52
	v_fmac_f32_e32 v59, v60, v60
	v_add_f32_e32 v50, v51, v50
	v_add_f32_e32 v58, v59, v58
	v_add_f32_e32 v50, v53, v50
	v_add_f32_e32 v50, v58, v50
	v_mov_b32_e32 v51, v50
	s_nop 1
	v_permlane16_swap_b32_e32 v51, v50
	s_waitcnt lgkmcnt(0)
	v_add_f32_e32 v50, v50, v51
	v_mov_b32_e32 v51, v50
	s_nop 1
	v_permlane32_swap_b32_e32 v51, v50
	s_and_saveexec_b64 s[22:23], s[38:39]
	s_cbranch_execz .LBB0_1376
	s_waitcnt lgkmcnt(0)
	v_add_f32_e32 v50, v50, v51
	ds_write_b32 v164, v50

; #define LAS __attribute__((address_space(3)))
; DI float shx(float v, int m, int lane) { return __builtin_bit_cast(float, __builtin_amdgcn_ds_bpermute((lane ^ m) << 2, __builtin_bit_cast(int, v))); }
;     DI void operator()(const f32x4 (&acc)[2][2][4][2], const pg8::Unit& u, int wr, int wc, int fr, int fq) const {
;     ...
;                     sq += (a[0] * a[0] + a[1] * a[1]) + (a[2] * a[2] + a[3] * a[3]) + (b[0] * b[0] + b[1] * b[1]) + (b[2] * b[2] + b[3] * b[3]);
;                 }
;                 if (ssout) { const int lane_ = fq * 16 + fr; sq += shx(sq, 16, lane_); sq += shx(sq, 32, lane_);
;                     if (fq == 0) *(LAS float*)(red + ((ai * 128 + wr * 64 + m * 16 + fr) * 4 + wc) * 4) = sq; }
.LBB0_1383:
	s_and_b64 vcc, exec, s[4:5]
	s_cbranch_vccnz .LBB0_1387
	v_mul_f32_e32 v47, v47, v47
	v_fmac_f32_e32 v47, v46, v46
	v_mul_f32_e32 v46, v49, v49
	v_mul_f32_e32 v37, v37, v37
	v_mul_f32_e32 v35, v35, v35
	v_fmac_f32_e32 v46, v48, v48
	v_mul_f32_e32 v43, v43, v43
	v_fmac_f32_e32 v37, v36, v36
	v_fmac_f32_e32 v35, v34, v34
	v_mul_f32_e32 v34, v39, v39
	v_mul_f32_e32 v36, v41, v41
	v_add_f32_e32 v46, v47, v46
	v_fmac_f32_e32 v43, v42, v42
	v_fmac_f32_e32 v34, v38, v38
	v_fmac_f32_e32 v36, v40, v40
	v_add_f32_e32 v42, v43, v46
	v_mul_f32_e32 v43, v45, v45
	v_add_f32_e32 v34, v34, v36
	v_fmac_f32_e32 v43, v44, v44
	v_add_f32_e32 v34, v35, v34
	v_add_f32_e32 v42, v43, v42
	v_add_f32_e32 v34, v37, v34
	v_add_f32_e32 v34, v42, v34
	v_mov_b32_e32 v35, v34
	s_nop 1
	v_permlane16_swap_b32_e32 v35, v34
	s_waitcnt lgkmcnt(0)
	v_add_f32_e32 v34, v34, v35
	v_mov_b32_e32 v35, v34
	s_nop 1
	v_permlane32_swap_b32_e32 v35, v34
	s_and_saveexec_b64 s[22:23], s[38:39]
	s_cbranch_execz .LBB0_1386
	s_waitcnt lgkmcnt(0)
	v_add_f32_e32 v34, v34, v35
	v_add_u32_e32 v35, s35, v159
	ds_write_b32 v35, v34 offset:2304

; #define LAS __attribute__((address_space(3)))
; DI float shx(float v, int m, int lane) { return __builtin_bit_cast(float, __builtin_amdgcn_ds_bpermute((lane ^ m) << 2, __builtin_bit_cast(int, v))); }
;     DI void operator()(const f32x4 (&acc)[2][2][4][2], const pg8::Unit& u, int wr, int wc, int fr, int fq) const {
;     ...
;                     sq += (a[0] * a[0] + a[1] * a[1]) + (a[2] * a[2] + a[3] * a[3]) + (b[0] * b[0] + b[1] * b[1]) + (b[2] * b[2] + b[3] * b[3]);
;                 }
;                 if (ssout) { const int lane_ = fq * 16 + fr; sq += shx(sq, 16, lane_); sq += shx(sq, 32, lane_);
;                     if (fq == 0) *(LAS float*)(red + ((ai * 128 + wr * 64 + m * 16 + fr) * 4 + wc) * 4) = sq; }
.LBB0_1393:
	s_and_b64 vcc, exec, s[4:5]
	s_cbranch_vccnz .LBB0_1397
	v_mul_f32_e32 v31, v31, v31
	v_fmac_f32_e32 v31, v30, v30
	v_mul_f32_e32 v30, v33, v33
	v_mul_f32_e32 v21, v21, v21
	v_mul_f32_e32 v19, v19, v19
	v_fmac_f32_e32 v30, v32, v32
	v_mul_f32_e32 v27, v27, v27
	v_fmac_f32_e32 v21, v20, v20
	v_fmac_f32_e32 v19, v18, v18
	v_mul_f32_e32 v18, v23, v23
	v_mul_f32_e32 v20, v25, v25
	v_add_f32_e32 v30, v31, v30
	v_fmac_f32_e32 v27, v26, v26
	v_fmac_f32_e32 v18, v22, v22
	v_fmac_f32_e32 v20, v24, v24
	v_add_f32_e32 v26, v27, v30
	v_mul_f32_e32 v27, v29, v29
	v_add_f32_e32 v18, v18, v20
	v_fmac_f32_e32 v27, v28, v28
	v_add_f32_e32 v18, v19, v18
	v_add_f32_e32 v26, v27, v26
	v_add_f32_e32 v18, v21, v18
	v_add_f32_e32 v18, v26, v18
	v_mov_b32_e32 v19, v18
	s_nop 1
	v_permlane16_swap_b32_e32 v19, v18
	s_waitcnt lgkmcnt(0)
	v_add_f32_e32 v18, v18, v19
	v_mov_b32_e32 v19, v18
	s_nop 1
	v_permlane32_swap_b32_e32 v19, v18
	s_and_saveexec_b64 s[22:23], s[38:39]
	s_cbranch_execz .LBB0_1396
	s_waitcnt lgkmcnt(0)
	v_add_f32_e32 v18, v18, v19
	v_add_u32_e32 v19, s35, v159
	ds_write_b32 v19, v18 offset:2560

; #define LAS __attribute__((address_space(3)))
; DI float shx(float v, int m, int lane) { return __builtin_bit_cast(float, __builtin_amdgcn_ds_bpermute((lane ^ m) << 2, __builtin_bit_cast(int, v))); }
;     DI void operator()(const f32x4 (&acc)[2][2][4][2], const pg8::Unit& u, int wr, int wc, int fr, int fq) const {
;     ...
;                     sq += (a[0] * a[0] + a[1] * a[1]) + (a[2] * a[2] + a[3] * a[3]) + (b[0] * b[0] + b[1] * b[1]) + (b[2] * b[2] + b[3] * b[3]);
;                 }
;                 if (ssout) { const int lane_ = fq * 16 + fr; sq += shx(sq, 16, lane_); sq += shx(sq, 32, lane_);
;                     if (fq == 0) *(LAS float*)(red + ((ai * 128 + wr * 64 + m * 16 + fr) * 4 + wc) * 4) = sq; }
.LBB0_1405:
	v_mul_f32_e32 v15, v15, v15
	v_fmac_f32_e32 v15, v14, v14
	v_mul_f32_e32 v14, v17, v17
	v_mul_f32_e32 v5, v5, v5
	v_mul_f32_e32 v3, v3, v3
	v_fmac_f32_e32 v14, v16, v16
	v_mul_f32_e32 v11, v11, v11
	v_fmac_f32_e32 v5, v4, v4
	v_fmac_f32_e32 v3, v2, v2
	v_mul_f32_e32 v2, v7, v7
	v_mul_f32_e32 v4, v9, v9
	v_add_f32_e32 v14, v15, v14
	v_fmac_f32_e32 v11, v10, v10
	v_fmac_f32_e32 v2, v6, v6
	v_fmac_f32_e32 v4, v8, v8
	v_add_f32_e32 v10, v11, v14
	v_mul_f32_e32 v11, v13, v13
	v_add_f32_e32 v2, v2, v4
	v_fmac_f32_e32 v11, v12, v12
	v_add_f32_e32 v2, v3, v2
	v_add_f32_e32 v10, v11, v10
	v_add_f32_e32 v2, v5, v2
	v_add_f32_e32 v2, v10, v2
	v_mov_b32_e32 v3, v2
	s_nop 1
	v_permlane16_swap_b32_e32 v3, v2
	s_waitcnt lgkmcnt(0)
	v_add_f32_e32 v2, v2, v3
	v_mov_b32_e32 v3, v2
	s_nop 1
	v_permlane32_swap_b32_e32 v3, v2
	s_and_saveexec_b64 s[2:3], s[38:39]
	s_cbranch_execz .LBB0_1407
	s_waitcnt lgkmcnt(0)
	v_add_f32_e32 v2, v2, v3
	v_add_u32_e32 v3, s35, v159
	ds_write_b32 v3, v2 offset:2816
